# E4e + waves 4-7 run their softmax section at s_setprio 2 (scalar-guarded) so the lagging wave outranks its SIMD partner there
# speedup vs baseline: 1.0019x; 1.0019x over previous
.Lmla_dma1_ret:
	ds_read_b128 v[80:83], v227 offset:32768
	ds_read_b128 v[84:87], v227 offset:40960
	ds_read_b128 v[88:91], v228 offset:32768
	ds_read_b128 v[92:95], v228 offset:40960
	s_add_i32 s16, s82, 0xffffff80
	s_add_i32 s14, s82, 0xffffffbf
	s_setprio 1
	ds_read_b128 v[232:235], v229 offset:32768
	ds_read_b128 v[236:239], v229 offset:40960
	s_waitcnt lgkmcnt(5)
	v_mfma_f32_32x32x16_bf16 v[112:127], v[80:83], v[130:133], v[64:79]
	s_waitcnt lgkmcnt(4)
	v_mfma_f32_32x32x16_bf16 v[96:111], v[84:87], v[130:133], v[64:79]
	ds_read_b128 v[80:83], v230 offset:32768
	ds_read_b128 v[84:87], v230 offset:40960
	s_waitcnt lgkmcnt(5)
	v_mfma_f32_32x32x16_bf16 v[112:127], v[88:91], v[134:137], v[112:127]
	s_waitcnt lgkmcnt(4)
	v_mfma_f32_32x32x16_bf16 v[96:111], v[92:95], v[134:137], v[96:111]
	ds_read_b128 v[88:91], v227 offset:32896
	ds_read_b128 v[92:95], v227 offset:41088
	s_waitcnt lgkmcnt(5)
	v_mfma_f32_32x32x16_bf16 v[112:127], v[232:235], v[138:141], v[112:127]
	s_waitcnt lgkmcnt(4)
	v_mfma_f32_32x32x16_bf16 v[96:111], v[236:239], v[138:141], v[96:111]
	ds_read_b128 v[232:235], v228 offset:32896
	ds_read_b128 v[236:239], v228 offset:41088
	s_waitcnt lgkmcnt(5)
	v_mfma_f32_32x32x16_bf16 v[112:127], v[80:83], v[142:145], v[112:127]
	s_waitcnt lgkmcnt(4)
	v_mfma_f32_32x32x16_bf16 v[96:111], v[84:87], v[142:145], v[96:111]
	ds_read_b128 v[80:83], v229 offset:32896
	ds_read_b128 v[84:87], v229 offset:41088
	s_waitcnt lgkmcnt(5)
	v_mfma_f32_32x32x16_bf16 v[112:127], v[88:91], v[162:165], v[112:127]
	s_waitcnt lgkmcnt(4)
	v_mfma_f32_32x32x16_bf16 v[96:111], v[92:95], v[162:165], v[96:111]
	ds_read_b128 v[88:91], v230 offset:32896
	ds_read_b128 v[92:95], v230 offset:41088
	s_waitcnt lgkmcnt(5)
	v_mfma_f32_32x32x16_bf16 v[112:127], v[232:235], v[166:169], v[112:127]
	s_waitcnt lgkmcnt(4)
	v_mfma_f32_32x32x16_bf16 v[96:111], v[236:239], v[166:169], v[96:111]
	v_add_u32_e32 v178, v187, v220
	ds_read_b128 v[232:235], v178 offset:4096
	ds_read_b128 v[236:239], v178
	ds_read_b128 v[240:243], v213
	s_waitcnt lgkmcnt(6)
	v_mfma_f32_32x32x16_bf16 v[112:127], v[80:83], v[170:173], v[112:127]
	s_waitcnt lgkmcnt(5)
	v_mfma_f32_32x32x16_bf16 v[96:111], v[84:87], v[170:173], v[96:111]
	v_add_u32_e32 v84, v187, v221
	ds_read_b128 v[80:83], v84 offset:4096
	ds_read_b128 v[84:87], v84
	ds_read_b128 v[244:247], v213 offset:1024
	s_waitcnt lgkmcnt(7)
	v_mfma_f32_32x32x16_bf16 v[112:127], v[88:91], v[174:177], v[112:127]
	s_waitcnt lgkmcnt(6)
	v_mfma_f32_32x32x16_bf16 v[96:111], v[92:95], v[174:177], v[96:111]
	v_add_u32_e32 v92, v187, v222
	ds_read_b128 v[88:91], v92 offset:4096
	ds_read_b128 v[92:95], v92
	ds_read_b128 v[248:251], v213 offset:2048
	s_waitcnt lgkmcnt(6)
	v_mfma_f32_32x32x16_bf16 v[112:127], v[236:239], v[240:243], v[112:127]
	v_mfma_f32_32x32x16_bf16 v[96:111], v[232:235], v[240:243], v[96:111]
	v_add_u32_e32 v178, v187, v223
	ds_read_b128 v[232:235], v178 offset:4096
	ds_read_b128 v[236:239], v178
	ds_read_b128 v[240:243], v213 offset:3072
	s_waitcnt lgkmcnt(6)
	v_mfma_f32_32x32x16_bf16 v[112:127], v[84:87], v[244:247], v[112:127]
	v_mfma_f32_32x32x16_bf16 v[96:111], v[80:83], v[244:247], v[96:111]
	s_waitcnt lgkmcnt(3)
	v_mfma_f32_32x32x16_bf16 v[112:127], v[92:95], v[248:251], v[112:127]
	v_mfma_f32_32x32x16_bf16 v[96:111], v[88:91], v[248:251], v[96:111]
	s_waitcnt lgkmcnt(0)
	v_mfma_f32_32x32x16_bf16 v[112:127], v[236:239], v[240:243], v[112:127]
	v_mfma_f32_32x32x16_bf16 v[96:111], v[232:235], v[240:243], v[96:111]
	s_setprio 0
	s_cmp_ge_u32 s3, 0x100
	s_cbranch_scc0 .Lmla_smprio_1
	s_setprio 2
.Lmla_smprio_1:
	s_cmp_le_i32 s14, s12
	s_cselect_b64 s[14:15], -1, 0
	s_cmp_gt_i32 s16, s22
	s_cselect_b64 s[44:45], -1, 0
	s_and_b64 s[14:15], s[14:15], s[44:45]
	s_and_b64 vcc, exec, s[14:15]
	s_cbranch_vccnz .LBB0_830
	v_add_u32_e32 v80, 59, v225
	v_cmp_gt_u32_e32 vcc, s35, v80
	v_add_u32_e32 v80, 27, v225
	s_nop 0
	v_cndmask_b32_e32 v112, v202, v112, vcc
	v_cmp_gt_u32_e32 vcc, s35, v80
	v_add_u32_e32 v80, 58, v225
	s_nop 0
	v_cndmask_b32_e32 v96, v202, v96, vcc
	v_cmp_gt_u32_e32 vcc, s35, v80
	v_add_u32_e32 v80, 26, v225
	s_nop 0
	v_cndmask_b32_e32 v113, v202, v113, vcc
	v_cmp_gt_u32_e32 vcc, s35, v80
	v_add_u32_e32 v80, 57, v225
	s_nop 0
	v_cndmask_b32_e32 v97, v202, v97, vcc
	v_cmp_gt_u32_e32 vcc, s35, v80
	v_add_u32_e32 v80, 25, v225
	s_nop 0
	v_cndmask_b32_e32 v114, v202, v114, vcc
	v_cmp_gt_u32_e32 vcc, s35, v80
	v_add_u32_e32 v80, 56, v225
	s_nop 0
	v_cndmask_b32_e32 v98, v202, v98, vcc
	v_cmp_gt_u32_e32 vcc, s35, v80
	v_add_u32_e32 v80, 24, v225
	s_nop 0
	v_cndmask_b32_e32 v115, v202, v115, vcc
	v_cmp_gt_u32_e32 vcc, s35, v80
	v_add_u32_e32 v80, 51, v225
	s_nop 0
	v_cndmask_b32_e32 v99, v202, v99, vcc
	v_cmp_gt_u32_e32 vcc, s35, v80
	v_add_u32_e32 v80, 19, v225
	s_nop 0
	v_cndmask_b32_e32 v116, v202, v116, vcc
	v_cmp_gt_u32_e32 vcc, s35, v80
	v_add_u32_e32 v80, 50, v225
	s_nop 0
	v_cndmask_b32_e32 v100, v202, v100, vcc
	v_cmp_gt_u32_e32 vcc, s35, v80
	v_add_u32_e32 v80, 18, v225
	s_nop 0
	v_cndmask_b32_e32 v117, v202, v117, vcc
	v_cmp_gt_u32_e32 vcc, s35, v80
	v_add_u32_e32 v80, 49, v225
	s_nop 0
	v_cndmask_b32_e32 v101, v202, v101, vcc
	v_cmp_gt_u32_e32 vcc, s35, v80
	v_add_u32_e32 v80, 17, v225
	s_nop 0
	v_cndmask_b32_e32 v118, v202, v118, vcc
	v_cmp_gt_u32_e32 vcc, s35, v80
	v_add_u32_e32 v80, 48, v225
	s_nop 0
	v_cndmask_b32_e32 v102, v202, v102, vcc
	v_cmp_gt_u32_e32 vcc, s35, v80
	v_add_u32_e32 v80, 16, v225
	s_nop 0
	v_cndmask_b32_e32 v119, v202, v119, vcc
	v_cmp_gt_u32_e32 vcc, s35, v80
	v_add_u32_e32 v80, 43, v225
	s_nop 0
	v_cndmask_b32_e32 v103, v202, v103, vcc
	v_cmp_gt_u32_e32 vcc, s35, v80
	v_add_u32_e32 v80, 11, v225
	s_nop 0
	v_cndmask_b32_e32 v120, v202, v120, vcc
	v_cmp_gt_u32_e32 vcc, s35, v80
	v_add_u32_e32 v80, 42, v225
	s_nop 0
	v_cndmask_b32_e32 v104, v202, v104, vcc
	v_cmp_gt_u32_e32 vcc, s35, v80
	v_add_u32_e32 v80, 10, v225
	s_nop 0
	v_cndmask_b32_e32 v121, v202, v121, vcc
	v_cmp_gt_u32_e32 vcc, s35, v80
	v_add_u32_e32 v80, 41, v225
	s_nop 0
	v_cndmask_b32_e32 v105, v202, v105, vcc
	v_cmp_gt_u32_e32 vcc, s35, v80
	v_add_u32_e32 v80, 9, v225
	s_nop 0
	v_cndmask_b32_e32 v122, v202, v122, vcc
	v_cmp_gt_u32_e32 vcc, s35, v80
	v_add_u32_e32 v80, 40, v225
	s_nop 0
	v_cndmask_b32_e32 v106, v202, v106, vcc
	v_cmp_gt_u32_e32 vcc, s35, v80
	v_add_u32_e32 v80, 8, v225
	s_nop 0
	v_cndmask_b32_e32 v123, v202, v123, vcc
	v_cmp_gt_u32_e32 vcc, s35, v80
	v_add_u32_e32 v80, 35, v225
	s_nop 0
	v_cndmask_b32_e32 v107, v202, v107, vcc
	v_cmp_gt_u32_e32 vcc, s35, v80
	v_add_u32_e32 v80, 3, v225
	s_nop 0
	v_cndmask_b32_e32 v124, v202, v124, vcc
	v_cmp_gt_u32_e32 vcc, s35, v80
	v_add_u32_e32 v80, 34, v225
	s_nop 0
	v_cndmask_b32_e32 v108, v202, v108, vcc
	v_cmp_gt_u32_e32 vcc, s35, v80
	v_add_u32_e32 v80, 2, v225
	s_nop 0
	v_cndmask_b32_e32 v125, v202, v125, vcc
	v_cmp_gt_u32_e32 vcc, s35, v80
	v_add_u32_e32 v80, 33, v225
	s_nop 0
	v_cndmask_b32_e32 v109, v202, v109, vcc
	v_cmp_gt_u32_e32 vcc, s35, v80
	v_add_u32_e32 v80, 1, v225
	s_nop 0
	v_cndmask_b32_e32 v126, v202, v126, vcc
	v_cmp_gt_u32_e32 vcc, s35, v80
	v_add_u32_e32 v80, 32, v225
	s_nop 0
	v_cndmask_b32_e32 v110, v202, v110, vcc
	v_cmp_gt_u32_e32 vcc, s35, v80
	s_nop 1
	v_cndmask_b32_e32 v127, v202, v127, vcc
	v_cmp_gt_u32_e32 vcc, s35, v225
	s_nop 1
	v_cndmask_b32_e32 v111, v202, v111, vcc

.LBB0_844:
	ds_read_b128 v[114:117], v227 offset:49152
	ds_read_b128 v[118:121], v227 offset:57344
	ds_read_b128 v[122:125], v228 offset:49152
	ds_read_b128 v[232:235], v228 offset:57344
	s_add_i32 s14, s82, -1
	s_setprio 1
	ds_read_b128 v[236:239], v229 offset:49152
	ds_read_b128 v[240:243], v229 offset:57344
	s_waitcnt lgkmcnt(5)
	v_mfma_f32_32x32x16_bf16 v[96:111], v[114:117], v[130:133], v[64:79]
	s_waitcnt lgkmcnt(4)
	v_mfma_f32_32x32x16_bf16 v[80:95], v[118:121], v[130:133], v[64:79]
	ds_read_b128 v[114:117], v230 offset:49152
	ds_read_b128 v[118:121], v230 offset:57344
	s_waitcnt lgkmcnt(5)
	v_mfma_f32_32x32x16_bf16 v[96:111], v[122:125], v[134:137], v[96:111]
	s_waitcnt lgkmcnt(4)
	v_mfma_f32_32x32x16_bf16 v[80:95], v[232:235], v[134:137], v[80:95]
	ds_read_b128 v[122:125], v227 offset:49280
	ds_read_b128 v[232:235], v227 offset:57472
	s_waitcnt lgkmcnt(5)
	v_mfma_f32_32x32x16_bf16 v[96:111], v[236:239], v[138:141], v[96:111]
	s_waitcnt lgkmcnt(4)
	v_mfma_f32_32x32x16_bf16 v[80:95], v[240:243], v[138:141], v[80:95]
	ds_read_b128 v[236:239], v228 offset:49280
	ds_read_b128 v[240:243], v228 offset:57472
	s_waitcnt lgkmcnt(5)
	v_mfma_f32_32x32x16_bf16 v[96:111], v[114:117], v[142:145], v[96:111]
	s_waitcnt lgkmcnt(4)
	v_mfma_f32_32x32x16_bf16 v[80:95], v[118:121], v[142:145], v[80:95]
	ds_read_b128 v[114:117], v229 offset:49280
	ds_read_b128 v[118:121], v229 offset:57472
	s_waitcnt lgkmcnt(5)
	v_mfma_f32_32x32x16_bf16 v[96:111], v[122:125], v[162:165], v[96:111]
	s_waitcnt lgkmcnt(4)
	v_mfma_f32_32x32x16_bf16 v[80:95], v[232:235], v[162:165], v[80:95]
	ds_read_b128 v[122:125], v230 offset:49280
	ds_read_b128 v[232:235], v230 offset:57472
	s_waitcnt lgkmcnt(5)
	v_mfma_f32_32x32x16_bf16 v[96:111], v[236:239], v[166:169], v[96:111]
	s_waitcnt lgkmcnt(4)
	v_mfma_f32_32x32x16_bf16 v[80:95], v[240:243], v[166:169], v[80:95]
	v_add_u32_e32 v126, v224, v220
	ds_read_b128 v[236:239], v126 offset:4096
	ds_read_b128 v[240:243], v126
	ds_read_b128 v[244:247], v213
	s_waitcnt lgkmcnt(6)
	v_mfma_f32_32x32x16_bf16 v[96:111], v[114:117], v[170:173], v[96:111]
	s_waitcnt lgkmcnt(5)
	v_mfma_f32_32x32x16_bf16 v[80:95], v[118:121], v[170:173], v[80:95]
	v_add_u32_e32 v118, v224, v221
	ds_read_b128 v[114:117], v118 offset:4096
	ds_read_b128 v[118:121], v118
	ds_read_b128 v[248:251], v213 offset:1024
	s_waitcnt lgkmcnt(7)
	v_mfma_f32_32x32x16_bf16 v[96:111], v[122:125], v[174:177], v[96:111]
	s_waitcnt lgkmcnt(6)
	v_mfma_f32_32x32x16_bf16 v[80:95], v[232:235], v[174:177], v[80:95]
	v_add_u32_e32 v126, v224, v222
	ds_read_b128 v[122:125], v126 offset:4096
	ds_read_b128 v[232:235], v126
	ds_read_b128 v[178:181], v213 offset:2048
	s_waitcnt lgkmcnt(6)
	v_mfma_f32_32x32x16_bf16 v[96:111], v[240:243], v[244:247], v[96:111]
	v_mfma_f32_32x32x16_bf16 v[80:95], v[236:239], v[244:247], v[80:95]
	v_add_u32_e32 v126, v224, v223
	ds_read_b128 v[236:239], v126 offset:4096
	ds_read_b128 v[240:243], v126
	ds_read_b128 v[244:247], v213 offset:3072
	s_waitcnt lgkmcnt(6)
	v_mfma_f32_32x32x16_bf16 v[96:111], v[118:121], v[248:251], v[96:111]
	v_mfma_f32_32x32x16_bf16 v[80:95], v[114:117], v[248:251], v[80:95]
	s_waitcnt lgkmcnt(3)
	v_mfma_f32_32x32x16_bf16 v[96:111], v[232:235], v[178:181], v[96:111]
	v_mfma_f32_32x32x16_bf16 v[80:95], v[122:125], v[178:181], v[80:95]
	s_waitcnt lgkmcnt(0)
	v_mfma_f32_32x32x16_bf16 v[96:111], v[240:243], v[244:247], v[96:111]
	v_mfma_f32_32x32x16_bf16 v[80:95], v[236:239], v[244:247], v[80:95]
	s_setprio 0
	s_cmp_ge_u32 s3, 0x100
	s_cbranch_scc0 .Lmla_smprio_2
	s_setprio 2
.Lmla_smprio_2:
	s_cmp_le_i32 s14, s12
	s_cselect_b64 s[14:15], -1, 0
	s_cmp_gt_i32 s50, s22
	s_cselect_b64 s[44:45], -1, 0
	s_and_b64 s[14:15], s[14:15], s[44:45]
	s_and_b64 vcc, exec, s[14:15]
	s_cbranch_vccnz .LBB0_846
	v_add_u32_e32 v114, -5, v225
	v_cmp_gt_u32_e32 vcc, s35, v114
	v_subrev_u32_e32 v114, 37, v225
	s_nop 0
	v_cndmask_b32_e32 v96, v202, v96, vcc
	v_cmp_gt_u32_e32 vcc, s35, v114
	v_add_u32_e32 v114, -6, v225
	s_nop 0
	v_cndmask_b32_e32 v80, v202, v80, vcc
	v_cmp_gt_u32_e32 vcc, s35, v114
	v_subrev_u32_e32 v114, 38, v225
	s_nop 0
	v_cndmask_b32_e32 v97, v202, v97, vcc
	v_cmp_gt_u32_e32 vcc, s35, v114
	v_add_u32_e32 v114, -7, v225
	s_nop 0
	v_cndmask_b32_e32 v81, v202, v81, vcc
	v_cmp_gt_u32_e32 vcc, s35, v114
	v_subrev_u32_e32 v114, 39, v225
	s_nop 0
	v_cndmask_b32_e32 v98, v202, v98, vcc
	v_cmp_gt_u32_e32 vcc, s35, v114
	v_add_u32_e32 v114, -8, v225
	s_nop 0
	v_cndmask_b32_e32 v82, v202, v82, vcc
	v_cmp_gt_u32_e32 vcc, s35, v114
	v_subrev_u32_e32 v114, 40, v225
	s_nop 0
	v_cndmask_b32_e32 v99, v202, v99, vcc
	v_cmp_gt_u32_e32 vcc, s35, v114
	v_add_u32_e32 v114, -13, v225
	s_nop 0
	v_cndmask_b32_e32 v83, v202, v83, vcc
	v_cmp_gt_u32_e32 vcc, s35, v114
	v_subrev_u32_e32 v114, 45, v225
	s_nop 0
	v_cndmask_b32_e32 v100, v202, v100, vcc
	v_cmp_gt_u32_e32 vcc, s35, v114
	v_add_u32_e32 v114, -14, v225
	s_nop 0
	v_cndmask_b32_e32 v84, v202, v84, vcc
	v_cmp_gt_u32_e32 vcc, s35, v114
	v_subrev_u32_e32 v114, 46, v225
	s_nop 0
	v_cndmask_b32_e32 v101, v202, v101, vcc
	v_cmp_gt_u32_e32 vcc, s35, v114
	v_add_u32_e32 v114, -15, v225
	s_nop 0
	v_cndmask_b32_e32 v85, v202, v85, vcc
	v_cmp_gt_u32_e32 vcc, s35, v114
	v_subrev_u32_e32 v114, 47, v225
	s_nop 0
	v_cndmask_b32_e32 v102, v202, v102, vcc
	v_cmp_gt_u32_e32 vcc, s35, v114
	v_add_u32_e32 v114, -16, v225
	s_nop 0
	v_cndmask_b32_e32 v86, v202, v86, vcc
	v_cmp_gt_u32_e32 vcc, s35, v114
	v_subrev_u32_e32 v114, 48, v225
	s_nop 0
	v_cndmask_b32_e32 v103, v202, v103, vcc
	v_cmp_gt_u32_e32 vcc, s35, v114
	v_subrev_u32_e32 v114, 21, v225
	s_nop 0
	v_cndmask_b32_e32 v87, v202, v87, vcc
	v_cmp_gt_u32_e32 vcc, s35, v114
	v_subrev_u32_e32 v114, 53, v225
	s_nop 0
	v_cndmask_b32_e32 v104, v202, v104, vcc
	v_cmp_gt_u32_e32 vcc, s35, v114
	v_subrev_u32_e32 v114, 22, v225
	s_nop 0
	v_cndmask_b32_e32 v88, v202, v88, vcc
	v_cmp_gt_u32_e32 vcc, s35, v114
	v_subrev_u32_e32 v114, 54, v225
	s_nop 0
	v_cndmask_b32_e32 v105, v202, v105, vcc
	v_cmp_gt_u32_e32 vcc, s35, v114
	v_subrev_u32_e32 v114, 23, v225
	s_nop 0
	v_cndmask_b32_e32 v89, v202, v89, vcc
	v_cmp_gt_u32_e32 vcc, s35, v114
	v_subrev_u32_e32 v114, 55, v225
	s_nop 0
	v_cndmask_b32_e32 v106, v202, v106, vcc
	v_cmp_gt_u32_e32 vcc, s35, v114
	v_subrev_u32_e32 v114, 24, v225
	s_nop 0
	v_cndmask_b32_e32 v90, v202, v90, vcc
	v_cmp_gt_u32_e32 vcc, s35, v114
	v_subrev_u32_e32 v114, 56, v225
	s_nop 0
	v_cndmask_b32_e32 v107, v202, v107, vcc
	v_cmp_gt_u32_e32 vcc, s35, v114
	v_subrev_u32_e32 v114, 29, v225
	s_nop 0
	v_cndmask_b32_e32 v91, v202, v91, vcc
	v_cmp_gt_u32_e32 vcc, s35, v114
	v_subrev_u32_e32 v114, 61, v225
	s_nop 0
	v_cndmask_b32_e32 v108, v202, v108, vcc
	v_cmp_gt_u32_e32 vcc, s35, v114
	v_subrev_u32_e32 v114, 30, v225
	s_nop 0
	v_cndmask_b32_e32 v92, v202, v92, vcc
	v_cmp_gt_u32_e32 vcc, s35, v114
	v_subrev_u32_e32 v114, 62, v225
	s_nop 0
	v_cndmask_b32_e32 v109, v202, v109, vcc
	v_cmp_gt_u32_e32 vcc, s35, v114
	v_subrev_u32_e32 v114, 31, v225
	s_nop 0
	v_cndmask_b32_e32 v93, v202, v93, vcc
	v_cmp_gt_u32_e32 vcc, s35, v114
	v_subrev_u32_e32 v114, 63, v225
	s_nop 0
	v_cndmask_b32_e32 v110, v202, v110, vcc
	v_cmp_gt_u32_e32 vcc, s35, v114
	v_subrev_u32_e32 v114, 32, v225
	s_nop 0
	v_cndmask_b32_e32 v94, v202, v94, vcc
	v_cmp_gt_u32_e32 vcc, s35, v114
	v_subrev_u32_e32 v114, 64, v225
	s_nop 0
	v_cndmask_b32_e32 v111, v202, v111, vcc
	v_cmp_gt_u32_e32 vcc, s35, v114
	s_nop 1
	v_cndmask_b32_e32 v95, v202, v95, vcc
